# speedup vs baseline: 1.0064x; 1.0002x over previous
; __device__ __forceinline__ unsigned cvt_pk_bf16(float lo, float hi) { const f32x2 v = {lo, hi}; const bf16v2 r = __builtin_convertvector(v, bf16v2); return __builtin_bit_cast(unsigned, r); }
; __device__ __forceinline__ float bf_lo(unsigned u) { return __uint_as_float(u << 16); }
; __device__ __forceinline__ float bf_hi(unsigned u) { return __uint_as_float(u & 0xffff0000u); }
; __device__ __forceinline__ int otid() { int t = threadIdx.x; asm volatile("" : "+v"(t)); return t; }
; __device__ __forceinline__ int obid() { int b = blockIdx.x; asm volatile("" : "+s"(b)); return b; }
; __device__ void attn_combine(const bf16_t* AP, const float* LSE, bf16_t* MIX) {
;     ...
;     for (int i = obid() * 512 + otid(); i < n; i += gridDim.x * 512) {
;         const int tok = i >> 7, ch = i & 127, h = ch >> 4;
;         const float l0 = LSE[((size_t)0 * T + tok) * 8 + h], l1 = LSE[((size_t)1 * T + tok) * 8 + h], l2 = LSE[((size_t)2 * T + tok) * 8 + h];
;         const float m = fmaxf(l0, fmaxf(l1, l2)); float w0 = __expf(l0 - m), w1 = __expf(l1 - m), w2 = __expf(l2 - m); const float rs = 1.0f / (w0 + w1 + w2); w0 *= rs; w1 *= rs; w2 *= rs;
;         const u32x4 a = *(const u32x4*)(AP + ((size_t)0 * T + tok) * 1024 + ch * 8), b = *(const u32x4*)(AP + ((size_t)1 * T + tok) * 1024 + ch * 8), c = *(const u32x4*)(AP + ((size_t)2 * T + tok) * 1024 + ch * 8);
;         u32x4 w;
; #pragma unroll
;         for (int e = 0; e < 4; ++e) w[e] = cvt_pk_bf16(w0 * bf_lo(a[e]) + w1 * bf_lo(b[e]) + w2 * bf_lo(c[e]), w0 * bf_hi(a[e]) + w1 * bf_hi(b[e]) + w2 * bf_hi(c[e]));
;         *(u32x4*)(MIX + (size_t)tok * DM + ch * 8) = w;
.LBB0_297:
	v_ashrrev_i32_e32 v8, 7, v10
	v_ashrrev_i32_e32 v9, 31, v8
	v_lshlrev_b64 v[12:13], 5, v[8:9]
	s_mov_b64 s[4:5], 0x6000
	v_lshl_add_u64 v[12:13], v[2:3], 0, v[12:13]
	v_lshl_add_u64 v[16:17], v[8:9], 0, s[4:5]
	global_load_dword v0, v[12:13], off
	v_lshlrev_b64 v[12:13], 5, v[16:17]
	v_lshl_add_u64 v[12:13], v[2:3], 0, v[12:13]
	v_lshl_add_u64 v[20:21], v[8:9], 0, s[6:7]
	global_load_dword v11, v[12:13], off
	v_lshlrev_b64 v[12:13], 5, v[20:21]
	v_lshl_add_u64 v[12:13], v[2:3], 0, v[12:13]
	global_load_dword v12, v[12:13], off
	v_lshlrev_b64 v[20:21], 11, v[20:21]
	v_lshl_add_u64 v[20:21], v[4:5], 0, v[20:21]
	global_load_dwordx4 v[20:23], v[20:21], off
	v_lshlrev_b64 v[16:17], 11, v[16:17]
	v_lshl_add_u64 v[16:17], v[4:5], 0, v[16:17]
	v_lshlrev_b64 v[34:35], 11, v[8:9]
	v_lshl_add_u64 v[34:35], v[4:5], 0, v[34:35]
	global_load_dwordx4 v[36:39], v[34:35], off
	global_load_dwordx4 v[40:43], v[16:17], off
	v_add_u32_e32 v54, s67, v10
	v_cmp_gt_i32_e32 vcc, 0x300000, v54
	s_nop 1
	s_and_saveexec_b64 s[12:13], vcc
	v_ashrrev_i32_e32 v58, 7, v54
	v_ashrrev_i32_e32 v59, 31, v58
	v_lshlrev_b64 v[62:63], 5, v[58:59]
	s_mov_b64 s[4:5], 0x6000
	v_lshl_add_u64 v[62:63], v[2:3], 0, v[62:63]
	v_lshl_add_u64 v[66:67], v[58:59], 0, s[4:5]
	global_load_dword v50, v[62:63], off
	v_lshlrev_b64 v[62:63], 5, v[66:67]
	v_lshl_add_u64 v[62:63], v[2:3], 0, v[62:63]
	v_lshl_add_u64 v[70:71], v[58:59], 0, s[6:7]
	global_load_dword v61, v[62:63], off
	v_lshlrev_b64 v[62:63], 5, v[70:71]
	v_lshl_add_u64 v[62:63], v[2:3], 0, v[62:63]
	global_load_dword v62, v[62:63], off
	v_lshlrev_b64 v[70:71], 11, v[70:71]
	v_lshl_add_u64 v[70:71], v[4:5], 0, v[70:71]
	global_load_dwordx4 v[70:73], v[70:71], off
	v_lshlrev_b64 v[66:67], 11, v[66:67]
	v_lshl_add_u64 v[66:67], v[4:5], 0, v[66:67]
	v_lshlrev_b64 v[84:85], 11, v[58:59]
	v_lshl_add_u64 v[84:85], v[4:5], 0, v[84:85]
	global_load_dwordx4 v[86:89], v[84:85], off
	global_load_dwordx4 v[90:93], v[66:67], off
	s_mov_b64 exec, s[12:13]
	v_add_u32_e32 v10, s67, v54
	s_waitcnt vmcnt(9)
	v_max3_f32 v13, v0, v11, v12
	v_sub_f32_e32 v0, v0, v13
	v_mul_f32_e32 v0, 0x3fb8aa3b, v0
	v_exp_f32_e32 v25, v0
	v_sub_f32_e32 v0, v11, v13
	v_mul_f32_e32 v0, 0x3fb8aa3b, v0
	v_exp_f32_e32 v24, v0
	v_sub_f32_e32 v0, v12, v13
	v_mul_f32_e32 v0, 0x3fb8aa3b, v0
	v_exp_f32_e32 v11, v0
	v_add_f32_e32 v0, v25, v24
	s_waitcnt vmcnt(8)
	v_lshlrev_b32_e32 v32, 16, v20
	v_and_b32_e32 v33, 0xffff0000, v20
	v_add_f32_e32 v0, v11, v0
	v_div_scale_f32 v12, s[4:5], v0, v0, 1.0
	v_rcp_f32_e32 v13, v12
	v_lshlrev_b32_e32 v20, 16, v21
	v_and_b32_e32 v21, 0xffff0000, v21
	v_fma_f32 v14, -v12, v13, 1.0
	v_fmac_f32_e32 v13, v14, v13
	v_div_scale_f32 v14, vcc, 1.0, v0, 1.0
	v_mul_f32_e32 v15, v14, v13
	v_fma_f32 v18, -v12, v15, v14
	v_fmac_f32_e32 v15, v18, v13
	v_fma_f32 v12, -v12, v15, v14
	v_div_fmas_f32 v12, v12, v13, v15
	v_div_fixup_f32 v0, v12, v0, 1.0
	v_pk_mul_f32 v[24:25], v[24:25], v[0:1] op_sel_hi:[1,0]
	v_mul_f32_e32 v26, v11, v0
	v_lshlrev_b64 v[8:9], 12, v[8:9]
	v_lshl_add_u64 v[8:9], v[6:7], 0, v[8:9]
	s_waitcnt vmcnt(6)
	v_lshlrev_b32_e32 v30, 16, v36
	v_and_b32_e32 v29, 0xffff0000, v36
	s_waitcnt vmcnt(6)
; __device__ __forceinline__ unsigned cvt_pk_bf16(float lo, float hi) { const f32x2 v = {lo, hi}; const bf16v2 r = __builtin_convertvector(v, bf16v2); return __builtin_bit_cast(unsigned, r); }
; __device__ __forceinline__ float bf_lo(unsigned u) { return __uint_as_float(u << 16); }
; __device__ __forceinline__ float bf_hi(unsigned u) { return __uint_as_float(u & 0xffff0000u); }
; __device__ __forceinline__ int otid() { int t = threadIdx.x; asm volatile("" : "+v"(t)); return t; }
; __device__ __forceinline__ int obid() { int b = blockIdx.x; asm volatile("" : "+s"(b)); return b; }
; __device__ void attn_combine(const bf16_t* AP, const float* LSE, bf16_t* MIX) {
;     ...
;     for (int i = obid() * 512 + otid(); i < n; i += gridDim.x * 512) {
;         const int tok = i >> 7, ch = i & 127, h = ch >> 4;
;         const float l0 = LSE[((size_t)0 * T + tok) * 8 + h], l1 = LSE[((size_t)1 * T + tok) * 8 + h], l2 = LSE[((size_t)2 * T + tok) * 8 + h];
;         const float m = fmaxf(l0, fmaxf(l1, l2)); float w0 = __expf(l0 - m), w1 = __expf(l1 - m), w2 = __expf(l2 - m); const float rs = 1.0f / (w0 + w1 + w2); w0 *= rs; w1 *= rs; w2 *= rs;
;         const u32x4 a = *(const u32x4*)(AP + ((size_t)0 * T + tok) * 1024 + ch * 8), b = *(const u32x4*)(AP + ((size_t)1 * T + tok) * 1024 + ch * 8), c = *(const u32x4*)(AP + ((size_t)2 * T + tok) * 1024 + ch * 8);
;         u32x4 w;
; #pragma unroll
;         for (int e = 0; e < 4; ++e) w[e] = cvt_pk_bf16(w0 * bf_lo(a[e]) + w1 * bf_lo(b[e]) + w2 * bf_lo(c[e]), w0 * bf_hi(a[e]) + w1 * bf_hi(b[e]) + w2 * bf_hi(c[e]));
;         *(u32x4*)(MIX + (size_t)tok * DM + ch * 8) = w;
	v_and_b32_e32 v31, 0xffff0000, v40
	v_lshlrev_b32_e32 v28, 16, v40
	v_pk_mul_f32 v[30:31], v[24:25], v[30:31] op_sel:[1,0] op_sel_hi:[0,1]
	v_pk_fma_f32 v[28:29], v[24:25], v[28:29], v[30:31]
	v_lshlrev_b32_e32 v40, 16, v37
	v_pk_fma_f32 v[28:29], v[26:27], v[32:33], v[28:29] op_sel_hi:[0,1,1]
	v_cvt_pk_bf16_f32 v36, v28, v29
	v_lshlrev_b32_e32 v28, 16, v41
	v_and_b32_e32 v41, 0xffff0000, v41
	v_and_b32_e32 v29, 0xffff0000, v37
	v_pk_mul_f32 v[40:41], v[24:25], v[40:41] op_sel:[1,0] op_sel_hi:[0,1]
	v_pk_fma_f32 v[40:41], v[24:25], v[28:29], v[40:41]
	v_lshlrev_b32_e32 v28, 16, v22
	v_pk_fma_f32 v[40:41], v[26:27], v[20:21], v[40:41] op_sel_hi:[0,1,1]
	v_lshlrev_b32_e32 v20, 16, v38
	v_and_b32_e32 v21, 0xffff0000, v42
	v_cvt_pk_bf16_f32 v37, v40, v41
	v_lshlrev_b32_e32 v40, 16, v42
	v_and_b32_e32 v41, 0xffff0000, v38
	v_pk_mul_f32 v[20:21], v[24:25], v[20:21] op_sel:[1,0] op_sel_hi:[0,1]
	v_and_b32_e32 v29, 0xffff0000, v22
	v_pk_fma_f32 v[40:41], v[24:25], v[40:41], v[20:21]
	v_lshlrev_b32_e32 v42, 16, v39
	v_pk_fma_f32 v[40:41], v[26:27], v[28:29], v[40:41] op_sel_hi:[0,1,1]
	v_cvt_pk_bf16_f32 v38, v40, v41
	v_lshlrev_b32_e32 v40, 16, v43
	v_and_b32_e32 v43, 0xffff0000, v43
	v_and_b32_e32 v41, 0xffff0000, v39
	v_pk_mul_f32 v[42:43], v[24:25], v[42:43] op_sel:[1,0] op_sel_hi:[0,1]
	v_pk_fma_f32 v[40:41], v[24:25], v[40:41], v[42:43]
	v_lshlrev_b32_e32 v42, 16, v23
	v_and_b32_e32 v43, 0xffff0000, v23
	v_pk_fma_f32 v[40:41], v[26:27], v[42:43], v[40:41] op_sel_hi:[0,1,1]
	v_cvt_pk_bf16_f32 v39, v40, v41
	global_store_dwordx4 v[8:9], v[36:39], off
	s_waitcnt vmcnt(4)
	v_max3_f32 v63, v50, v61, v62
	v_sub_f32_e32 v50, v50, v63
	v_mul_f32_e32 v50, 0x3fb8aa3b, v50
	v_exp_f32_e32 v75, v50
	v_sub_f32_e32 v50, v61, v63
	v_mul_f32_e32 v50, 0x3fb8aa3b, v50
	v_exp_f32_e32 v74, v50
	v_sub_f32_e32 v50, v62, v63
	v_mul_f32_e32 v50, 0x3fb8aa3b, v50
	v_exp_f32_e32 v61, v50
	v_add_f32_e32 v50, v75, v74
	s_waitcnt vmcnt(3)
	v_lshlrev_b32_e32 v82, 16, v70
	v_and_b32_e32 v83, 0xffff0000, v70
	v_add_f32_e32 v50, v61, v50
	v_div_scale_f32 v62, s[4:5], v50, v50, 1.0
	v_rcp_f32_e32 v63, v62
	v_lshlrev_b32_e32 v70, 16, v71
	v_and_b32_e32 v71, 0xffff0000, v71
	v_fma_f32 v64, -v62, v63, 1.0
	v_fmac_f32_e32 v63, v64, v63
	v_div_scale_f32 v64, vcc, 1.0, v50, 1.0
	v_mul_f32_e32 v65, v64, v63
	v_fma_f32 v68, -v62, v65, v64
	v_fmac_f32_e32 v65, v68, v63
	v_fma_f32 v62, -v62, v65, v64
	v_div_fmas_f32 v62, v62, v63, v65
	v_div_fixup_f32 v50, v62, v50, 1.0
	v_pk_mul_f32 v[74:75], v[74:75], v[50:51] op_sel_hi:[1,0]
	v_mul_f32_e32 v76, v61, v50
	v_lshlrev_b64 v[58:59], 12, v[58:59]
	v_lshl_add_u64 v[58:59], v[6:7], 0, v[58:59]
	s_waitcnt vmcnt(1)
	v_lshlrev_b32_e32 v80, 16, v86
	v_and_b32_e32 v79, 0xffff0000, v86
	s_waitcnt vmcnt(1)
	v_and_b32_e32 v81, 0xffff0000, v90
	v_lshlrev_b32_e32 v78, 16, v90
	v_pk_mul_f32 v[80:81], v[74:75], v[80:81] op_sel:[1,0] op_sel_hi:[0,1]
	v_pk_fma_f32 v[78:79], v[74:75], v[78:79], v[80:81]
	v_lshlrev_b32_e32 v90, 16, v87
	v_pk_fma_f32 v[78:79], v[76:77], v[82:83], v[78:79] op_sel_hi:[0,1,1]
	v_cvt_pk_bf16_f32 v86, v78, v79
	v_lshlrev_b32_e32 v78, 16, v91
	v_and_b32_e32 v91, 0xffff0000, v91
	v_and_b32_e32 v79, 0xffff0000, v87
	v_pk_mul_f32 v[90:91], v[74:75], v[90:91] op_sel:[1,0] op_sel_hi:[0,1]
	v_pk_fma_f32 v[90:91], v[74:75], v[78:79], v[90:91]
	v_lshlrev_b32_e32 v78, 16, v72
	v_pk_fma_f32 v[90:91], v[76:77], v[70:71], v[90:91] op_sel_hi:[0,1,1]
	v_lshlrev_b32_e32 v70, 16, v88
	v_and_b32_e32 v71, 0xffff0000, v92
	v_cvt_pk_bf16_f32 v87, v90, v91
	v_lshlrev_b32_e32 v90, 16, v92
	v_and_b32_e32 v91, 0xffff0000, v88
	v_pk_mul_f32 v[70:71], v[74:75], v[70:71] op_sel:[1,0] op_sel_hi:[0,1]
	v_and_b32_e32 v79, 0xffff0000, v72
	v_pk_fma_f32 v[90:91], v[74:75], v[90:91], v[70:71]
	v_lshlrev_b32_e32 v92, 16, v89
	v_pk_fma_f32 v[90:91], v[76:77], v[78:79], v[90:91] op_sel_hi:[0,1,1]
	v_cvt_pk_bf16_f32 v88, v90, v91
	v_lshlrev_b32_e32 v90, 16, v93
	v_and_b32_e32 v93, 0xffff0000, v93
	v_and_b32_e32 v91, 0xffff0000, v89
	v_pk_mul_f32 v[92:93], v[74:75], v[92:93] op_sel:[1,0] op_sel_hi:[0,1]
	v_pk_fma_f32 v[90:91], v[74:75], v[90:91], v[92:93]
	v_lshlrev_b32_e32 v92, 16, v73
	v_and_b32_e32 v93, 0xffff0000, v73
	v_pk_fma_f32 v[90:91], v[76:77], v[92:93], v[90:91] op_sel_hi:[0,1,1]
	v_cvt_pk_bf16_f32 v89, v90, v91
	v_cmp_gt_i32_e32 vcc, 0x300000, v54
	s_nop 1
	s_and_saveexec_b64 s[12:13], vcc
	global_store_dwordx4 v[58:59], v[86:89], off
	s_mov_b64 exec, s[12:13]
	s_mov_b32 s4, 0x2fffff
	v_cmp_lt_i32_e32 vcc, s4, v10
	s_nop 1
	s_or_b64 s[2:3], vcc, s[2:3]
	s_andn2_b64 exec, exec, s[2:3]
	s_cbranch_execnz .LBB0_297
